# static s_setprio 1 for waves 4-7 during the MoBA and retention phases
# speedup vs baseline: 1.0000x; 1.0000x over previous
.LBB0_854:
	s_setprio 0
	v_readlane_b32 s28, v254, 56
	v_readlane_b32 s34, v254, 34
	s_mov_b64 s[4:5], 0
	v_readlane_b32 s2, v254, 33
	v_readlane_b32 s29, v254, 57
	v_readlane_b32 s35, v254, 35
	v_readlane_b32 s30, v254, 58
	v_readlane_b32 s31, v254, 59

.LBB0_859:
	v_readlane_b32 s4, v254, 60
	s_cmp_lt_u32 s4, 4
	s_cbranch_scc1 .Lprio_ret
	s_setprio 1

.LBB0_931:
	s_setprio 0
	v_readlane_b32 s28, v254, 56
	v_readlane_b32 s34, v254, 34
	v_readlane_b32 s2, v254, 33
	v_readlane_b32 s29, v254, 57
	v_readlane_b32 s35, v254, 35
	s_flbit_i32_b32 s85, 0
	v_readlane_b32 s30, v254, 58
	v_readlane_b32 s31, v254, 59
